# v41: grid barrier rewritten by hand: per-XCD arrival count, XCD leader flushes and bumps one top counter, all WGs poll the top counter (2 hops instead of 5); generation = instance index
# speedup vs baseline: 1.0101x; 1.0101x over previous
; __device__ __forceinline__ unsigned xb_ld(unsigned* p)              { return __hip_atomic_load(p, __ATOMIC_RELAXED, __HIP_MEMORY_SCOPE_AGENT); }
; __device__ __forceinline__ unsigned xb_add(unsigned* p, unsigned v) { return __hip_atomic_fetch_add(p, v, __ATOMIC_RELAXED, __HIP_MEMORY_SCOPE_AGENT); }
; #define XB_SPIN(cond, bar) do { unsigned _sp = 0; while (cond) { __builtin_amdgcn_s_sleep(1); \
;     if ((++_sp & 255u) == 0u) { if (xb_ld(&(bar)[XB_TMO])) break; if (_sp > XB_SPIN_CAP) { atomicAdd(&(bar)[XB_TMO], 1u); break; } } } } while (0)
; __device__ __forceinline__ void xcd_barrier(const XcdBarrier& b) {
;     asm volatile("s_waitcnt vmcnt(0)" ::: "memory");
;     __syncthreads();
;     if (threadIdx.x == 0) {
;         unsigned* bar = b.bar;
;         __builtin_amdgcn_s_waitcnt(0);
;         unsigned nloc = b.st[0], nx = b.st[1];
;         if (nloc == 0u) { xcd_barrier_complete(bar, b.x, nloc, nx); b.st[0] = nloc; b.st[1] = nx; }
;         const unsigned old = xb_add(&bar[XB_XSUB(b.x)], 1u);
;         const unsigned gen = old / nloc;
;         if (old + 1u == (gen + 1u) * nloc) {
;             __builtin_amdgcn_fence(__ATOMIC_RELEASE, "agent");
;             asm volatile("s_waitcnt vmcnt(0)" ::: "memory");
;             const unsigned og = xb_add(&bar[XB_TOP], 1u);
;             const unsigned tg = og / nx;
;             if (og + 1u == (tg + 1u) * nx) xb_add(&bar[XB_TOPGEN], 1u);
;             else XB_SPIN(xb_ld(&bar[XB_TOPGEN]) == tg, bar);
;             __builtin_amdgcn_fence(__ATOMIC_ACQUIRE, "agent");
;             xb_add(&bar[XB_XGEN(b.x)], 1u);
;             asm volatile("s_waitcnt vmcnt(0)" ::: "memory");
;         } else {
;             XB_SPIN(xb_ld(&bar[XB_XGEN(b.x)]) == gen, bar);
;             __builtin_amdgcn_fence(__ATOMIC_ACQUIRE, "agent");
;             asm volatile("s_waitcnt vmcnt(0)" ::: "memory");
;         }
;     }
;     __syncthreads();
; }
.LBB0_82:
	v_mov_b32_e32 v4, 0x20000
	ds_read2_b32 v[2:3], v4 offset1:1
	v_readlane_b32 s3, v244, 30
	s_nop 0
	s_lshl_b32 s3, s3, 8
	s_getpc_b64 s[4:5]
	s_add_u32 s4, s4, g_xbar@rel32@lo+4
	s_addc_u32 s5, s5, g_xbar@rel32@hi+12
	s_add_u32 s4, s4, s3
	s_addc_u32 s5, s5, 0
	v_mov_b32_e32 v5, 0x1000
	v_mov_b32_e32 v6, 1
	global_atomic_add v5, v5, v6, s[4:5] offset:1024 sc0
	s_movk_i32 s3, 1
	s_waitcnt lgkmcnt(0)
	v_mul_lo_u32 v2, v2, s3
	v_mul_lo_u32 v3, v3, s3
	s_waitcnt vmcnt(0)
	v_add_u32_e32 v5, 1, v5
	v_cmp_ne_u32_e32 vcc, v5, v2
	s_getpc_b64 s[4:5]
	s_add_u32 s4, s4, g_xbar@rel32@lo+13316
	s_addc_u32 s5, s5, g_xbar@rel32@hi+13324
	v_mov_b32_e32 v4, 0
	s_cbranch_vccnz .Lfb0_spin0
	buffer_wbl2 sc1
	s_waitcnt vmcnt(0) lgkmcnt(0)
	global_atomic_add v4, v6, s[4:5]
.Lfb0_spin0:
	s_mov_b32 s3, 0
.Lfb0_spin:
	global_load_dword v5, v4, s[4:5] sc1
	s_waitcnt vmcnt(0)
	v_cmp_ge_u32_e32 vcc, v5, v3
	s_cbranch_vccnz .Lfb0_done
	s_sleep 1
	s_add_u32 s3, s3, 1
	s_cmp_lt_u32 s3, 0x200000
	s_cbranch_scc1 .Lfb0_spin
.Lfb0_done:
	buffer_inv sc1
	s_waitcnt vmcnt(0)

; __device__ __forceinline__ unsigned xb_add(unsigned* p, unsigned v) { return __hip_atomic_fetch_add(p, v, __ATOMIC_RELAXED, __HIP_MEMORY_SCOPE_AGENT); }
; __device__ __forceinline__ void xcd_barrier(const XcdBarrier& b) {
;     asm volatile("s_waitcnt vmcnt(0)" ::: "memory");
;     __syncthreads();
;     if (threadIdx.x == 0) {
;         unsigned* bar = b.bar;
;         __builtin_amdgcn_s_waitcnt(0);
;         unsigned nloc = b.st[0], nx = b.st[1];
;         if (nloc == 0u) { xcd_barrier_complete(bar, b.x, nloc, nx); b.st[0] = nloc; b.st[1] = nx; }
;         const unsigned old = xb_add(&bar[XB_XSUB(b.x)], 1u);
;         const unsigned gen = old / nloc;
;         if (old + 1u == (gen + 1u) * nloc) {
;             __builtin_amdgcn_fence(__ATOMIC_RELEASE, "agent");
;             asm volatile("s_waitcnt vmcnt(0)" ::: "memory");
;             const unsigned og = xb_add(&bar[XB_TOP], 1u);
;             const unsigned tg = og / nx;
;             if (og + 1u == (tg + 1u) * nx) xb_add(&bar[XB_TOPGEN], 1u);
.LBB0_464:
	v_mov_b32_e32 v4, 0x20000
	ds_read2_b32 v[2:3], v4 offset1:1
	v_readlane_b32 s3, v244, 30
	s_nop 0
	s_lshl_b32 s3, s3, 8
	s_getpc_b64 s[4:5]
	s_add_u32 s4, s4, g_xbar@rel32@lo+4
	s_addc_u32 s5, s5, g_xbar@rel32@hi+12
	s_add_u32 s4, s4, s3
	s_addc_u32 s5, s5, 0
	v_mov_b32_e32 v5, 0x1000
	v_mov_b32_e32 v6, 1
	global_atomic_add v5, v5, v6, s[4:5] offset:1024 sc0
	s_movk_i32 s3, 2
	s_waitcnt lgkmcnt(0)
	v_mul_lo_u32 v2, v2, s3
	v_mul_lo_u32 v3, v3, s3
	s_waitcnt vmcnt(0)
	v_add_u32_e32 v5, 1, v5
	v_cmp_ne_u32_e32 vcc, v5, v2
	s_getpc_b64 s[4:5]
	s_add_u32 s4, s4, g_xbar@rel32@lo+13316
	s_addc_u32 s5, s5, g_xbar@rel32@hi+13324
	v_mov_b32_e32 v4, 0
	s_cbranch_vccnz .Lfb1_spin0
	buffer_wbl2 sc1
	s_waitcnt vmcnt(0) lgkmcnt(0)
	global_atomic_add v4, v6, s[4:5]

; __device__ __forceinline__ unsigned xb_ld(unsigned* p)              { return __hip_atomic_load(p, __ATOMIC_RELAXED, __HIP_MEMORY_SCOPE_AGENT); }
; __device__ __forceinline__ unsigned xb_add(unsigned* p, unsigned v) { return __hip_atomic_fetch_add(p, v, __ATOMIC_RELAXED, __HIP_MEMORY_SCOPE_AGENT); }
; #define XB_SPIN(cond, bar) do { unsigned _sp = 0; while (cond) { __builtin_amdgcn_s_sleep(1); \
;     if ((++_sp & 255u) == 0u) { if (xb_ld(&(bar)[XB_TMO])) break; if (_sp > XB_SPIN_CAP) { atomicAdd(&(bar)[XB_TMO], 1u); break; } } } } while (0)
; __device__ __forceinline__ void xcd_barrier(const XcdBarrier& b) {
;     asm volatile("s_waitcnt vmcnt(0)" ::: "memory");
;     __syncthreads();
;     if (threadIdx.x == 0) {
;         unsigned* bar = b.bar;
;         __builtin_amdgcn_s_waitcnt(0);
;         unsigned nloc = b.st[0], nx = b.st[1];
;         if (nloc == 0u) { xcd_barrier_complete(bar, b.x, nloc, nx); b.st[0] = nloc; b.st[1] = nx; }
;         const unsigned old = xb_add(&bar[XB_XSUB(b.x)], 1u);
;         const unsigned gen = old / nloc;
;         if (old + 1u == (gen + 1u) * nloc) {
;             __builtin_amdgcn_fence(__ATOMIC_RELEASE, "agent");
;             asm volatile("s_waitcnt vmcnt(0)" ::: "memory");
;             const unsigned og = xb_add(&bar[XB_TOP], 1u);
;             const unsigned tg = og / nx;
;             if (og + 1u == (tg + 1u) * nx) xb_add(&bar[XB_TOPGEN], 1u);
;             else XB_SPIN(xb_ld(&bar[XB_TOPGEN]) == tg, bar);
;             __builtin_amdgcn_fence(__ATOMIC_ACQUIRE, "agent");
;             xb_add(&bar[XB_XGEN(b.x)], 1u);
;             asm volatile("s_waitcnt vmcnt(0)" ::: "memory");
;         } else {
;             XB_SPIN(xb_ld(&bar[XB_XGEN(b.x)]) == gen, bar);
;             __builtin_amdgcn_fence(__ATOMIC_ACQUIRE, "agent");
;             asm volatile("s_waitcnt vmcnt(0)" ::: "memory");
;         }
.LBB0_594:
	v_mov_b32_e32 v4, 0x20000
	ds_read2_b32 v[2:3], v4 offset1:1
	v_readlane_b32 s6, v244, 30
	s_nop 0
	s_lshl_b32 s6, s6, 8
	s_getpc_b64 s[4:5]
	s_add_u32 s4, s4, g_xbar@rel32@lo+4
	s_addc_u32 s5, s5, g_xbar@rel32@hi+12
	s_add_u32 s4, s4, s6
	s_addc_u32 s5, s5, 0
	v_mov_b32_e32 v5, 0x1000
	v_mov_b32_e32 v6, 1
	global_atomic_add v5, v5, v6, s[4:5] offset:1024 sc0
	s_movk_i32 s6, 3
	s_waitcnt lgkmcnt(0)
	v_mul_lo_u32 v2, v2, s6
	v_mul_lo_u32 v3, v3, s6
	s_waitcnt vmcnt(0)
	v_add_u32_e32 v5, 1, v5
	v_cmp_ne_u32_e32 vcc, v5, v2
	s_getpc_b64 s[4:5]
	s_add_u32 s4, s4, g_xbar@rel32@lo+13316
	s_addc_u32 s5, s5, g_xbar@rel32@hi+13324
	v_mov_b32_e32 v4, 0
	s_cbranch_vccnz .Lfb2_spin0
	buffer_wbl2 sc1
	s_waitcnt vmcnt(0) lgkmcnt(0)
	global_atomic_add v4, v6, s[4:5]
.Lfb2_spin0:
	s_mov_b32 s6, 0
.Lfb2_spin:
	global_load_dword v5, v4, s[4:5] sc1
	s_waitcnt vmcnt(0)
	v_cmp_ge_u32_e32 vcc, v5, v3
	s_cbranch_vccnz .Lfb2_done
	s_sleep 1
	s_add_u32 s6, s6, 1
	s_cmp_lt_u32 s6, 0x200000
	s_cbranch_scc1 .Lfb2_spin

; __device__ __forceinline__ unsigned xb_add(unsigned* p, unsigned v) { return __hip_atomic_fetch_add(p, v, __ATOMIC_RELAXED, __HIP_MEMORY_SCOPE_AGENT); }
; __device__ __forceinline__ void xcd_barrier(const XcdBarrier& b) {
;     asm volatile("s_waitcnt vmcnt(0)" ::: "memory");
;     __syncthreads();
;     if (threadIdx.x == 0) {
;         unsigned* bar = b.bar;
;         __builtin_amdgcn_s_waitcnt(0);
;         unsigned nloc = b.st[0], nx = b.st[1];
;         if (nloc == 0u) { xcd_barrier_complete(bar, b.x, nloc, nx); b.st[0] = nloc; b.st[1] = nx; }
;         const unsigned old = xb_add(&bar[XB_XSUB(b.x)], 1u);
;         const unsigned gen = old / nloc;
;         if (old + 1u == (gen + 1u) * nloc) {
;             __builtin_amdgcn_fence(__ATOMIC_RELEASE, "agent");
;             asm volatile("s_waitcnt vmcnt(0)" ::: "memory");
;             const unsigned og = xb_add(&bar[XB_TOP], 1u);
;             const unsigned tg = og / nx;
;             if (og + 1u == (tg + 1u) * nx) xb_add(&bar[XB_TOPGEN], 1u);
.LBB0_684:
	v_mov_b32_e32 v4, 0x20000
	ds_read2_b32 v[2:3], v4 offset1:1
	v_readlane_b32 s6, v244, 30
	s_nop 0
	s_lshl_b32 s6, s6, 8
	s_getpc_b64 s[4:5]
	s_add_u32 s4, s4, g_xbar@rel32@lo+4
	s_addc_u32 s5, s5, g_xbar@rel32@hi+12
	s_add_u32 s4, s4, s6
	s_addc_u32 s5, s5, 0
	v_mov_b32_e32 v5, 0x1000
	v_mov_b32_e32 v6, 1
	global_atomic_add v5, v5, v6, s[4:5] offset:1024 sc0
	s_movk_i32 s6, 4
	s_waitcnt lgkmcnt(0)
	v_mul_lo_u32 v2, v2, s6
	v_mul_lo_u32 v3, v3, s6
	s_waitcnt vmcnt(0)
	v_add_u32_e32 v5, 1, v5
	v_cmp_ne_u32_e32 vcc, v5, v2
	s_getpc_b64 s[4:5]
	s_add_u32 s4, s4, g_xbar@rel32@lo+13316
	s_addc_u32 s5, s5, g_xbar@rel32@hi+13324
	v_mov_b32_e32 v4, 0
	s_cbranch_vccnz .Lfb3_spin0
	buffer_wbl2 sc1
	s_waitcnt vmcnt(0) lgkmcnt(0)
	global_atomic_add v4, v6, s[4:5]

; __device__ __forceinline__ unsigned xb_add(unsigned* p, unsigned v) { return __hip_atomic_fetch_add(p, v, __ATOMIC_RELAXED, __HIP_MEMORY_SCOPE_AGENT); }
; __device__ __forceinline__ void xcd_barrier(const XcdBarrier& b) {
;     asm volatile("s_waitcnt vmcnt(0)" ::: "memory");
;     __syncthreads();
;     if (threadIdx.x == 0) {
;         unsigned* bar = b.bar;
;         __builtin_amdgcn_s_waitcnt(0);
;         unsigned nloc = b.st[0], nx = b.st[1];
;         if (nloc == 0u) { xcd_barrier_complete(bar, b.x, nloc, nx); b.st[0] = nloc; b.st[1] = nx; }
;         const unsigned old = xb_add(&bar[XB_XSUB(b.x)], 1u);
;         const unsigned gen = old / nloc;
;         if (old + 1u == (gen + 1u) * nloc) {
;             __builtin_amdgcn_fence(__ATOMIC_RELEASE, "agent");
;             asm volatile("s_waitcnt vmcnt(0)" ::: "memory");
;             const unsigned og = xb_add(&bar[XB_TOP], 1u);
;             const unsigned tg = og / nx;
;             if (og + 1u == (tg + 1u) * nx) xb_add(&bar[XB_TOPGEN], 1u);
.LBB0_763:
	v_mov_b32_e32 v4, 0x20000
	ds_read2_b32 v[2:3], v4 offset1:1
	v_readlane_b32 s6, v244, 30
	s_nop 0
	s_lshl_b32 s6, s6, 8
	s_getpc_b64 s[4:5]
	s_add_u32 s4, s4, g_xbar@rel32@lo+4
	s_addc_u32 s5, s5, g_xbar@rel32@hi+12
	s_add_u32 s4, s4, s6
	s_addc_u32 s5, s5, 0
	v_mov_b32_e32 v5, 0x1000
	v_mov_b32_e32 v6, 1
	global_atomic_add v5, v5, v6, s[4:5] offset:1024 sc0
	s_movk_i32 s6, 5
	s_waitcnt lgkmcnt(0)
	v_mul_lo_u32 v2, v2, s6
	v_mul_lo_u32 v3, v3, s6
	s_waitcnt vmcnt(0)
	v_add_u32_e32 v5, 1, v5
	v_cmp_ne_u32_e32 vcc, v5, v2
	s_getpc_b64 s[4:5]
	s_add_u32 s4, s4, g_xbar@rel32@lo+13316
	s_addc_u32 s5, s5, g_xbar@rel32@hi+13324
	v_mov_b32_e32 v4, 0
	s_cbranch_vccnz .Lfb4_spin0
	buffer_wbl2 sc1
	s_waitcnt vmcnt(0) lgkmcnt(0)
	global_atomic_add v4, v6, s[4:5]

; __device__ __forceinline__ unsigned xb_add(unsigned* p, unsigned v) { return __hip_atomic_fetch_add(p, v, __ATOMIC_RELAXED, __HIP_MEMORY_SCOPE_AGENT); }
; __device__ __forceinline__ void xcd_barrier(const XcdBarrier& b) {
;     asm volatile("s_waitcnt vmcnt(0)" ::: "memory");
;     __syncthreads();
;     if (threadIdx.x == 0) {
;         unsigned* bar = b.bar;
;         __builtin_amdgcn_s_waitcnt(0);
;         unsigned nloc = b.st[0], nx = b.st[1];
;         if (nloc == 0u) { xcd_barrier_complete(bar, b.x, nloc, nx); b.st[0] = nloc; b.st[1] = nx; }
;         const unsigned old = xb_add(&bar[XB_XSUB(b.x)], 1u);
;         const unsigned gen = old / nloc;
;         if (old + 1u == (gen + 1u) * nloc) {
;             __builtin_amdgcn_fence(__ATOMIC_RELEASE, "agent");
;             asm volatile("s_waitcnt vmcnt(0)" ::: "memory");
;             const unsigned og = xb_add(&bar[XB_TOP], 1u);
;             const unsigned tg = og / nx;
;             if (og + 1u == (tg + 1u) * nx) xb_add(&bar[XB_TOPGEN], 1u);
.LBB0_853:
	v_mov_b32_e32 v4, 0x20000
	ds_read2_b32 v[2:3], v4 offset1:1
	v_readlane_b32 s6, v244, 30
	s_nop 0
	s_lshl_b32 s6, s6, 8
	s_getpc_b64 s[4:5]
	s_add_u32 s4, s4, g_xbar@rel32@lo+4
	s_addc_u32 s5, s5, g_xbar@rel32@hi+12
	s_add_u32 s4, s4, s6
	s_addc_u32 s5, s5, 0
	v_mov_b32_e32 v5, 0x1000
	v_mov_b32_e32 v6, 1
	global_atomic_add v5, v5, v6, s[4:5] offset:1024 sc0
	s_movk_i32 s6, 6
	s_waitcnt lgkmcnt(0)
	v_mul_lo_u32 v2, v2, s6
	v_mul_lo_u32 v3, v3, s6
	s_waitcnt vmcnt(0)
	v_add_u32_e32 v5, 1, v5
	v_cmp_ne_u32_e32 vcc, v5, v2
	s_getpc_b64 s[4:5]
	s_add_u32 s4, s4, g_xbar@rel32@lo+13316
	s_addc_u32 s5, s5, g_xbar@rel32@hi+13324
	v_mov_b32_e32 v4, 0
	s_cbranch_vccnz .Lfb5_spin0
	buffer_wbl2 sc1
	s_waitcnt vmcnt(0) lgkmcnt(0)
	global_atomic_add v4, v6, s[4:5]

; __device__ __forceinline__ unsigned xb_add(unsigned* p, unsigned v) { return __hip_atomic_fetch_add(p, v, __ATOMIC_RELAXED, __HIP_MEMORY_SCOPE_AGENT); }
; __device__ __forceinline__ void xcd_barrier(const XcdBarrier& b) {
;     asm volatile("s_waitcnt vmcnt(0)" ::: "memory");
;     __syncthreads();
;     if (threadIdx.x == 0) {
;         unsigned* bar = b.bar;
;         __builtin_amdgcn_s_waitcnt(0);
;         unsigned nloc = b.st[0], nx = b.st[1];
;         if (nloc == 0u) { xcd_barrier_complete(bar, b.x, nloc, nx); b.st[0] = nloc; b.st[1] = nx; }
;         const unsigned old = xb_add(&bar[XB_XSUB(b.x)], 1u);
;         const unsigned gen = old / nloc;
;         if (old + 1u == (gen + 1u) * nloc) {
;             __builtin_amdgcn_fence(__ATOMIC_RELEASE, "agent");
;             asm volatile("s_waitcnt vmcnt(0)" ::: "memory");
;             const unsigned og = xb_add(&bar[XB_TOP], 1u);
;             const unsigned tg = og / nx;
;             if (og + 1u == (tg + 1u) * nx) xb_add(&bar[XB_TOPGEN], 1u);
.LBB0_915:
	v_mov_b32_e32 v4, 0x20000
	ds_read2_b32 v[2:3], v4 offset1:1
	v_readlane_b32 s3, v244, 30
	s_nop 0
	s_lshl_b32 s3, s3, 8
	s_getpc_b64 s[8:9]
	s_add_u32 s8, s8, g_xbar@rel32@lo+4
	s_addc_u32 s9, s9, g_xbar@rel32@hi+12
	s_add_u32 s8, s8, s3
	s_addc_u32 s9, s9, 0
	v_mov_b32_e32 v5, 0x1000
	v_mov_b32_e32 v6, 1
	global_atomic_add v5, v5, v6, s[8:9] offset:1024 sc0
	s_movk_i32 s3, 7
	s_waitcnt lgkmcnt(0)
	v_mul_lo_u32 v2, v2, s3
	v_mul_lo_u32 v3, v3, s3
	s_waitcnt vmcnt(0)
	v_add_u32_e32 v5, 1, v5
	v_cmp_ne_u32_e32 vcc, v5, v2
	s_getpc_b64 s[8:9]
	s_add_u32 s8, s8, g_xbar@rel32@lo+13316
	s_addc_u32 s9, s9, g_xbar@rel32@hi+13324
	v_mov_b32_e32 v4, 0
	s_cbranch_vccnz .Lfb6_spin0
	buffer_wbl2 sc1
	s_waitcnt vmcnt(0) lgkmcnt(0)
	global_atomic_add v4, v6, s[8:9]

; __device__ __forceinline__ unsigned xb_ld(unsigned* p)              { return __hip_atomic_load(p, __ATOMIC_RELAXED, __HIP_MEMORY_SCOPE_AGENT); }
; __device__ __forceinline__ unsigned xb_add(unsigned* p, unsigned v) { return __hip_atomic_fetch_add(p, v, __ATOMIC_RELAXED, __HIP_MEMORY_SCOPE_AGENT); }
; #define XB_SPIN(cond, bar) do { unsigned _sp = 0; while (cond) { __builtin_amdgcn_s_sleep(1); \
;     if ((++_sp & 255u) == 0u) { if (xb_ld(&(bar)[XB_TMO])) break; if (_sp > XB_SPIN_CAP) { atomicAdd(&(bar)[XB_TMO], 1u); break; } } } } while (0)
; __device__ __forceinline__ void xcd_barrier(const XcdBarrier& b) {
;     ...
;             const unsigned og = xb_add(&bar[XB_TOP], 1u);
;             const unsigned tg = og / nx;
;             if (og + 1u == (tg + 1u) * nx) xb_add(&bar[XB_TOPGEN], 1u);
;             else XB_SPIN(xb_ld(&bar[XB_TOPGEN]) == tg, bar);
;             __builtin_amdgcn_fence(__ATOMIC_ACQUIRE, "agent");
;             xb_add(&bar[XB_XGEN(b.x)], 1u);
;             asm volatile("s_waitcnt vmcnt(0)" ::: "memory");
;         } else {
;             XB_SPIN(xb_ld(&bar[XB_XGEN(b.x)]) == gen, bar);
;             __builtin_amdgcn_fence(__ATOMIC_ACQUIRE, "agent");
;             asm volatile("s_waitcnt vmcnt(0)" ::: "memory");
;         }
.Lfb6_spin:
	global_load_dword v5, v4, s[8:9] sc1
	s_waitcnt vmcnt(0)
	v_cmp_ge_u32_e32 vcc, v5, v3
	s_cbranch_vccnz .Lfb6_done
	s_sleep 1
	s_add_u32 s3, s3, 1
	s_cmp_lt_u32 s3, 0x200000
	s_cbranch_scc1 .Lfb6_spin

; __device__ __forceinline__ unsigned xb_add(unsigned* p, unsigned v) { return __hip_atomic_fetch_add(p, v, __ATOMIC_RELAXED, __HIP_MEMORY_SCOPE_AGENT); }
; __device__ __forceinline__ void xcd_barrier(const XcdBarrier& b) {
;     asm volatile("s_waitcnt vmcnt(0)" ::: "memory");
;     __syncthreads();
;     if (threadIdx.x == 0) {
;         unsigned* bar = b.bar;
;         __builtin_amdgcn_s_waitcnt(0);
;         unsigned nloc = b.st[0], nx = b.st[1];
;         if (nloc == 0u) { xcd_barrier_complete(bar, b.x, nloc, nx); b.st[0] = nloc; b.st[1] = nx; }
;         const unsigned old = xb_add(&bar[XB_XSUB(b.x)], 1u);
;         const unsigned gen = old / nloc;
;         if (old + 1u == (gen + 1u) * nloc) {
;             __builtin_amdgcn_fence(__ATOMIC_RELEASE, "agent");
;             asm volatile("s_waitcnt vmcnt(0)" ::: "memory");
;             const unsigned og = xb_add(&bar[XB_TOP], 1u);
;             const unsigned tg = og / nx;
;             if (og + 1u == (tg + 1u) * nx) xb_add(&bar[XB_TOPGEN], 1u);
.LBB0_1119:
	v_mov_b32_e32 v4, 0x20000
	ds_read2_b32 v[2:3], v4 offset1:1
	v_readlane_b32 s3, v244, 30
	s_nop 0
	s_lshl_b32 s3, s3, 8
	s_getpc_b64 s[8:9]
	s_add_u32 s8, s8, g_xbar@rel32@lo+4
	s_addc_u32 s9, s9, g_xbar@rel32@hi+12
	s_add_u32 s8, s8, s3
	s_addc_u32 s9, s9, 0
	v_mov_b32_e32 v5, 0x1000
	v_mov_b32_e32 v6, 1
	global_atomic_add v5, v5, v6, s[8:9] offset:1024 sc0
	s_movk_i32 s3, 8
	s_waitcnt lgkmcnt(0)
	v_mul_lo_u32 v2, v2, s3
	v_mul_lo_u32 v3, v3, s3
	s_waitcnt vmcnt(0)
	v_add_u32_e32 v5, 1, v5
	v_cmp_ne_u32_e32 vcc, v5, v2
	s_getpc_b64 s[8:9]
	s_add_u32 s8, s8, g_xbar@rel32@lo+13316
	s_addc_u32 s9, s9, g_xbar@rel32@hi+13324
	v_mov_b32_e32 v4, 0
	s_cbranch_vccnz .Lfb7_spin0
	buffer_wbl2 sc1
	s_waitcnt vmcnt(0) lgkmcnt(0)
	global_atomic_add v4, v6, s[8:9]

; __device__ __forceinline__ unsigned xb_ld(unsigned* p)              { return __hip_atomic_load(p, __ATOMIC_RELAXED, __HIP_MEMORY_SCOPE_AGENT); }
; __device__ __forceinline__ unsigned xb_add(unsigned* p, unsigned v) { return __hip_atomic_fetch_add(p, v, __ATOMIC_RELAXED, __HIP_MEMORY_SCOPE_AGENT); }
; #define XB_SPIN(cond, bar) do { unsigned _sp = 0; while (cond) { __builtin_amdgcn_s_sleep(1); \
;     if ((++_sp & 255u) == 0u) { if (xb_ld(&(bar)[XB_TMO])) break; if (_sp > XB_SPIN_CAP) { atomicAdd(&(bar)[XB_TMO], 1u); break; } } } } while (0)
; __device__ __forceinline__ void xcd_barrier(const XcdBarrier& b) {
;     asm volatile("s_waitcnt vmcnt(0)" ::: "memory");
;     __syncthreads();
;     if (threadIdx.x == 0) {
;         unsigned* bar = b.bar;
;         __builtin_amdgcn_s_waitcnt(0);
;         unsigned nloc = b.st[0], nx = b.st[1];
;         if (nloc == 0u) { xcd_barrier_complete(bar, b.x, nloc, nx); b.st[0] = nloc; b.st[1] = nx; }
;         const unsigned old = xb_add(&bar[XB_XSUB(b.x)], 1u);
;         const unsigned gen = old / nloc;
;         if (old + 1u == (gen + 1u) * nloc) {
;             __builtin_amdgcn_fence(__ATOMIC_RELEASE, "agent");
;             asm volatile("s_waitcnt vmcnt(0)" ::: "memory");
;             const unsigned og = xb_add(&bar[XB_TOP], 1u);
;             const unsigned tg = og / nx;
;             if (og + 1u == (tg + 1u) * nx) xb_add(&bar[XB_TOPGEN], 1u);
;             else XB_SPIN(xb_ld(&bar[XB_TOPGEN]) == tg, bar);
;             __builtin_amdgcn_fence(__ATOMIC_ACQUIRE, "agent");
;             xb_add(&bar[XB_XGEN(b.x)], 1u);
;             asm volatile("s_waitcnt vmcnt(0)" ::: "memory");
;         } else {
;             XB_SPIN(xb_ld(&bar[XB_XGEN(b.x)]) == gen, bar);
;             __builtin_amdgcn_fence(__ATOMIC_ACQUIRE, "agent");
;             asm volatile("s_waitcnt vmcnt(0)" ::: "memory");
;         }
;     }
;     __syncthreads();
.LBB0_1180:
	v_mov_b32_e32 v1, 0x20000
	ds_read2_b32 v[2:3], v1 offset1:1
	v_readlane_b32 s8, v244, 30
	s_nop 0
	s_lshl_b32 s8, s8, 8
	s_getpc_b64 s[6:7]
	s_add_u32 s6, s6, g_xbar@rel32@lo+4
	s_addc_u32 s7, s7, g_xbar@rel32@hi+12
	s_add_u32 s6, s6, s8
	s_addc_u32 s7, s7, 0
	v_mov_b32_e32 v4, 0x1000
	v_mov_b32_e32 v5, 1
	global_atomic_add v4, v4, v5, s[6:7] offset:1024 sc0
	s_movk_i32 s8, 9
	s_waitcnt lgkmcnt(0)
	v_mul_lo_u32 v2, v2, s8
	v_mul_lo_u32 v3, v3, s8
	s_waitcnt vmcnt(0)
	v_add_u32_e32 v4, 1, v4
	v_cmp_ne_u32_e32 vcc, v4, v2
	s_getpc_b64 s[6:7]
	s_add_u32 s6, s6, g_xbar@rel32@lo+13316
	s_addc_u32 s7, s7, g_xbar@rel32@hi+13324
	v_mov_b32_e32 v1, 0
	s_cbranch_vccnz .Lfb8_spin0
	buffer_wbl2 sc1
	s_waitcnt vmcnt(0) lgkmcnt(0)
	global_atomic_add v1, v5, s[6:7]
.Lfb8_spin0:
	s_mov_b32 s8, 0
.Lfb8_spin:
	global_load_dword v4, v1, s[6:7] sc1
	s_waitcnt vmcnt(0)
	v_cmp_ge_u32_e32 vcc, v4, v3
	s_cbranch_vccnz .Lfb8_done
	s_sleep 1
	s_add_u32 s8, s8, 1
	s_cmp_lt_u32 s8, 0x200000
	s_cbranch_scc1 .Lfb8_spin

; __device__ __forceinline__ unsigned xb_ld(unsigned* p)              { return __hip_atomic_load(p, __ATOMIC_RELAXED, __HIP_MEMORY_SCOPE_AGENT); }
; __device__ __forceinline__ unsigned xb_add(unsigned* p, unsigned v) { return __hip_atomic_fetch_add(p, v, __ATOMIC_RELAXED, __HIP_MEMORY_SCOPE_AGENT); }
; #define XB_SPIN(cond, bar) do { unsigned _sp = 0; while (cond) { __builtin_amdgcn_s_sleep(1); \
;     if ((++_sp & 255u) == 0u) { if (xb_ld(&(bar)[XB_TMO])) break; if (_sp > XB_SPIN_CAP) { atomicAdd(&(bar)[XB_TMO], 1u); break; } } } } while (0)
; __device__ __forceinline__ void xcd_barrier(const XcdBarrier& b) {
;     asm volatile("s_waitcnt vmcnt(0)" ::: "memory");
;     __syncthreads();
;     if (threadIdx.x == 0) {
;         unsigned* bar = b.bar;
;         __builtin_amdgcn_s_waitcnt(0);
;         unsigned nloc = b.st[0], nx = b.st[1];
;         if (nloc == 0u) { xcd_barrier_complete(bar, b.x, nloc, nx); b.st[0] = nloc; b.st[1] = nx; }
;         const unsigned old = xb_add(&bar[XB_XSUB(b.x)], 1u);
;         const unsigned gen = old / nloc;
;         if (old + 1u == (gen + 1u) * nloc) {
;             __builtin_amdgcn_fence(__ATOMIC_RELEASE, "agent");
;             asm volatile("s_waitcnt vmcnt(0)" ::: "memory");
;             const unsigned og = xb_add(&bar[XB_TOP], 1u);
;             const unsigned tg = og / nx;
;             if (og + 1u == (tg + 1u) * nx) xb_add(&bar[XB_TOPGEN], 1u);
;             else XB_SPIN(xb_ld(&bar[XB_TOPGEN]) == tg, bar);
;             __builtin_amdgcn_fence(__ATOMIC_ACQUIRE, "agent");
;             xb_add(&bar[XB_XGEN(b.x)], 1u);
;             asm volatile("s_waitcnt vmcnt(0)" ::: "memory");
.LBB0_1274:
	v_mov_b32_e32 v2, 0x20000
	ds_read2_b32 v[0:1], v2 offset1:1
	v_readlane_b32 s8, v244, 30
	s_nop 0
	s_lshl_b32 s8, s8, 8
	s_getpc_b64 s[6:7]
	s_add_u32 s6, s6, g_xbar@rel32@lo+4
	s_addc_u32 s7, s7, g_xbar@rel32@hi+12
	s_add_u32 s6, s6, s8
	s_addc_u32 s7, s7, 0
	v_mov_b32_e32 v3, 0x1000
	v_mov_b32_e32 v4, 1
	global_atomic_add v3, v3, v4, s[6:7] offset:1024 sc0
	s_movk_i32 s8, 10
	s_waitcnt lgkmcnt(0)
	v_mul_lo_u32 v0, v0, s8
	v_mul_lo_u32 v1, v1, s8
	s_waitcnt vmcnt(0)
	v_add_u32_e32 v3, 1, v3
	v_cmp_ne_u32_e32 vcc, v3, v0
	s_getpc_b64 s[6:7]
	s_add_u32 s6, s6, g_xbar@rel32@lo+13316
	s_addc_u32 s7, s7, g_xbar@rel32@hi+13324
	v_mov_b32_e32 v2, 0
	s_cbranch_vccnz .Lfb9_spin0
	buffer_wbl2 sc1
	s_waitcnt vmcnt(0) lgkmcnt(0)
	global_atomic_add v2, v4, s[6:7]

; __device__ __forceinline__ unsigned xb_ld(unsigned* p)              { return __hip_atomic_load(p, __ATOMIC_RELAXED, __HIP_MEMORY_SCOPE_AGENT); }
; #define XB_SPIN(cond, bar) do { unsigned _sp = 0; while (cond) { __builtin_amdgcn_s_sleep(1); \
;     if ((++_sp & 255u) == 0u) { if (xb_ld(&(bar)[XB_TMO])) break; if (_sp > XB_SPIN_CAP) { atomicAdd(&(bar)[XB_TMO], 1u); break; } } } } while (0)
; __device__ __forceinline__ void xcd_barrier(const XcdBarrier& b) {
;     ...
;             else XB_SPIN(xb_ld(&bar[XB_TOPGEN]) == tg, bar);
.Lfb9_spin:
	global_load_dword v3, v2, s[6:7] sc1
	s_waitcnt vmcnt(0)
	v_cmp_ge_u32_e32 vcc, v3, v1
	s_cbranch_vccnz .Lfb9_done
	s_sleep 1
	s_add_u32 s8, s8, 1
	s_cmp_lt_u32 s8, 0x200000
	s_cbranch_scc1 .Lfb9_spin
